# system-scope streaming policy (sc0 sc1 nt) also on the sample SB cache stream and the out-proj residual (x) loads
# speedup vs baseline: 1.0203x; 1.0075x over previous
; #define LDS_AS __attribute__((address_space(3)))
;     ...
;     const float* ck = (MODE == 0 ? p.cak : p.cbk) + (size_t)bb * PAST * 512;
;     const float* cv = (MODE == 0 ? p.cav : p.cbv) + (size_t)bb * PAST * 512;
;     const int ntc = (MODE == 1 ? (PAST / NSPLIT / 32) : 128), kbase = (MODE == 1 ? (PAST / NSPLIT) * split : 0);
;     const bool has_new = (MODE == 0) || (split == NSPLIT - 1);
;     const float* cseq = p.c2s + (size_t)(bb * 8 + ((tid >> 5) & 7)) * LSK;
;     float cref = 0.f;
;     if (MODE == 1 && tid < 256) cref = cseq[PAST];
;     constexpr int KOFF = 0, VOFF = 36864, BOFF = 73728, HSTR = 4608;
;     bool wdone = false, alldone = false;
;     if (has_new) {
;         __syncthreads();
;         const bf16_t* kb = p.u + ((size_t)ROWS_P + bb * 32) * NU + segb + 512;
; #pragma unroll
;         for (int i = 0; i < 4; ++i) {
;             const int id = tid + 512 * i, r = id >> 6, c = id & 63, hd = c >> 3, d = (c & 7) * 8;
;             const u32x4 kx = *(const u32x4*)(kb + (size_t)r * NU + c * 8);
;             const u32x4 vx = *(const u32x4*)(kb + (size_t)r * NU + 512 + c * 8);
;             *(LDS_AS u32x4*)(lb + KOFF + hd * HSTR + r * 144 + d * 2) = kx;
;             *(LDS_AS u32x4*)(lb + VOFF + hd * HSTR + r * 144 + d * 2) = vx;
;         }
;         if (MODE == 1 && tid < 256) *(LDS_AS float*)(lb + BOFF + tid * 4) = cref - cseq[PAST + (tid & 31)];
;         __syncthreads();
;         attn_subtile<MODE>(lb + KOFF + wave * HSTR, lb + VOFF + wave * HSTR, lb + BOFF + wave * 128, q, st, PAST, qpos, true, lane);
;         if (MODE == 0) { wdone = __all(st.l < -SB_THRESH); alldone = __syncthreads_and(wdone ? 1 : 0) != 0; }
;     }
;     if (!alldone) {
;         f32x4 tk[8], tv[8]; float tb = 0.f;
;         const int rot = (MODE == 1) ? ((bb * NSPLIT + split) * 5) % ntc : 0;
;         {
;             const int t0i = (ntc - 1 + rot) % ntc;
;             const float* kg = ck + (size_t)(kbase + 32 * t0i) * 512;
;             const float* vg = cv + (size_t)(kbase + 32 * t0i) * 512;
;             if (MODE == 1 && tid < 256) tb = cseq[kbase + 32 * t0i + (tid & 31)];
; #pragma unroll
;             for (int i = 0; i < 8; ++i) { const int id = tid + 512 * i; tk[i] = __builtin_nontemporal_load((const f32x4*)(kg + (size_t)id * 4)); tv[i] = __builtin_nontemporal_load((const f32x4*)(vg + (size_t)id * 4)); }
;         }
.LBB0_493:
	s_ashr_i32 s31, s30, 31
	s_lshl_b64 s[4:5], s[30:31], 23
	s_add_u32 s10, s80, s4
	s_addc_u32 s39, s81, s5
	s_add_u32 s42, s82, s4
	s_addc_u32 s43, s83, s5
	s_add_u32 s4, s10, 0x7f0000
	s_addc_u32 s5, s39, 0
	s_add_u32 s30, s42, 0x7f0000
	v_ashrrev_i32_e32 v33, 31, v32
	v_add_u32_e32 v148, 0xe00, v32
	s_addc_u32 s31, s43, 0
	v_lshlrev_b64 v[40:41], 4, v[32:33]
	v_ashrrev_i32_e32 v149, 31, v148
	v_lshl_add_u64 v[44:45], s[4:5], 0, v[40:41]
	v_lshl_add_u64 v[40:41], s[30:31], 0, v[40:41]
	v_ashrrev_i32_e32 v35, 31, v34
	v_lshlrev_b64 v[124:125], 4, v[148:149]
	global_load_dwordx4 v[68:71], v[40:41], off sc0 sc1 nt
	v_lshlrev_b64 v[40:41], 4, v[34:35]
	v_lshl_add_u64 v[120:121], s[4:5], 0, v[124:125]
	global_load_dwordx4 v[64:67], v[44:45], off sc0 sc1 nt
	v_ashrrev_i32_e32 v37, 31, v36
	global_load_dwordx4 v[120:123], v[120:121], off sc0 sc1 nt
	v_lshl_add_u64 v[44:45], s[4:5], 0, v[40:41]
	v_lshl_add_u64 v[40:41], s[30:31], 0, v[40:41]
	global_load_dwordx4 v[76:79], v[40:41], off sc0 sc1 nt
	v_lshlrev_b64 v[40:41], 4, v[36:37]
	global_load_dwordx4 v[72:75], v[44:45], off sc0 sc1 nt
	v_lshl_add_u64 v[44:45], s[4:5], 0, v[40:41]
	v_lshl_add_u64 v[40:41], s[30:31], 0, v[40:41]
	v_ashrrev_i32_e32 v39, 31, v38
	global_load_dwordx4 v[84:87], v[40:41], off sc0 sc1 nt
	v_lshlrev_b64 v[40:41], 4, v[38:39]
	global_load_dwordx4 v[80:83], v[44:45], off sc0 sc1 nt
	v_lshl_add_u64 v[44:45], s[4:5], 0, v[40:41]
	v_lshl_add_u64 v[40:41], s[30:31], 0, v[40:41]
	global_load_dwordx4 v[92:95], v[40:41], off sc0 sc1 nt
	v_add_u32_e32 v40, 0x800, v32
	v_ashrrev_i32_e32 v41, 31, v40
	global_load_dwordx4 v[88:91], v[44:45], off sc0 sc1 nt
	v_lshlrev_b64 v[44:45], 4, v[40:41]
	v_lshl_add_u64 v[46:47], s[4:5], 0, v[44:45]
	v_lshl_add_u64 v[44:45], s[30:31], 0, v[44:45]
	global_load_dwordx4 v[100:103], v[44:45], off sc0 sc1 nt
	v_add_u32_e32 v44, 0xa00, v32
	v_ashrrev_i32_e32 v45, 31, v44
	global_load_dwordx4 v[96:99], v[46:47], off sc0 sc1 nt
	v_lshlrev_b64 v[46:47], 4, v[44:45]
	v_lshl_add_u64 v[104:105], s[4:5], 0, v[46:47]
	v_lshl_add_u64 v[46:47], s[30:31], 0, v[46:47]
	global_load_dwordx4 v[108:111], v[46:47], off sc0 sc1 nt
	v_add_u32_e32 v46, 0xc00, v32
	v_ashrrev_i32_e32 v47, 31, v46
	v_lshlrev_b64 v[116:117], 4, v[46:47]
	v_lshl_add_u64 v[112:113], s[4:5], 0, v[116:117]
	v_lshl_add_u64 v[116:117], s[30:31], 0, v[116:117]
	v_lshl_add_u64 v[124:125], s[30:31], 0, v[124:125]
	global_load_dwordx4 v[104:107], v[104:105], off sc0 sc1 nt
	v_add_f32_e32 v177, 0, v42
	global_load_dwordx4 v[112:115], v[112:113], off sc0 sc1 nt
	v_lshlrev_b64 v[42:43], 2, v[32:33]
	global_load_dwordx4 v[116:119], v[116:117], off sc0 sc1 nt
	v_lshlrev_b64 v[150:151], 2, v[34:35]
	global_load_dwordx4 v[124:127], v[124:125], off sc0 sc1 nt
	v_bfe_u32 v33, v32, 4, 3
	v_lshlrev_b32_e32 v35, 3, v32
	v_and_b32_e32 v35, 0x78, v35
	v_mul_u32_u24_e32 v33, 0x1200, v33
	v_add3_u32 v33, s62, v33, v35
	v_mad_u32_u24 v35, v141, s7, v143
	v_mad_u64_u32 v[178:179], s[4:5], v35, s6, v[138:139]
	v_lshrrev_b32_e32 v35, 6, v178
	v_or_b32_e32 v35, v35, v174
	v_lshlrev_b64 v[152:153], 2, v[36:37]
	v_lshlrev_b64 v[154:155], 2, v[38:39]
	v_lshlrev_b64 v[156:157], 2, v[40:41]
	v_cmp_eq_u32_e64 s[4:5], 0, v35
	v_ashrrev_i32_e32 v32, 7, v32
	v_ashrrev_i32_e32 v34, 7, v34
	v_ashrrev_i32_e32 v35, 7, v36
	v_ashrrev_i32_e32 v36, 7, v38
	v_ashrrev_i32_e32 v37, 7, v40
	v_ashrrev_i32_e32 v38, 7, v44
	v_ashrrev_i32_e32 v39, 7, v46
	v_ashrrev_i32_e32 v40, 7, v148
	v_lshlrev_b64 v[158:159], 2, v[44:45]
	v_lshlrev_b64 v[160:161], 2, v[46:47]
	v_lshlrev_b64 v[162:163], 2, v[148:149]
	v_cmp_eq_u32_e32 vcc, 0, v174
	v_cmp_lt_u32_e64 s[6:7], 63, v178
	v_mul_lo_u32 v32, v32, s89
	v_mul_lo_u32 v34, v34, s89
	v_mul_lo_u32 v35, v35, s89
	v_mul_lo_u32 v36, v36, s89
	v_mul_lo_u32 v37, v37, s89
	v_mul_lo_u32 v38, v38, s89
	v_mul_lo_u32 v39, v39, s89
	v_mul_lo_u32 v40, v40, s89
	s_and_b64 s[6:7], vcc, s[6:7]
	s_mov_b32 s46, 0x3f8000
	v_add_u32_e32 v178, v33, v32
	v_add_u32_e32 v179, v33, v34
	v_add_u32_e32 v180, v33, v35
	v_add_u32_e32 v181, v33, v36
	v_add_u32_e32 v182, v33, v37
	v_add_u32_e32 v183, v33, v38
	v_add_u32_e32 v184, v33, v39
	v_add_u32_e32 v185, v33, v40
	v_lshlrev_b64 v[148:149], 2, v[42:43]
	v_lshlrev_b64 v[150:151], 2, v[150:151]
	v_lshlrev_b64 v[152:153], 2, v[152:153]
	v_lshlrev_b64 v[154:155], 2, v[154:155]
	v_lshlrev_b64 v[156:157], 2, v[156:157]
	v_lshlrev_b64 v[158:159], 2, v[158:159]
	v_lshlrev_b64 v[160:161], 2, v[160:161]
	v_lshlrev_b64 v[162:163], 2, v[162:163]
	s_branch .LBB0_496

; #define LDS_AS __attribute__((address_space(3)))
; DI unsigned pk2(float a, float b) { f32x2 v = {a, b}; bf16x2v r = __builtin_convertvector(v, bf16x2v); return __builtin_bit_cast(unsigned, r); }
;     ...
;             const int kpos0 = kbase + 32 * ((it + rot) % ntc);
;             const int kposn = kbase + 32 * ((it - 1 + rot + ntc) % ntc);
;             __syncthreads();
; #pragma unroll
;             for (int i = 0; i < 8; ++i) {
;                 const int id = tid + 512 * i, r = id >> 7, c4 = id & 127, hd = c4 >> 4, d = (c4 & 15) * 4;
;                 *(LDS_AS u32x2*)(lb + KOFF + hd * HSTR + r * 144 + d * 2) = (u32x2){pk2(tk[i][0], tk[i][1]), pk2(tk[i][2], tk[i][3])};
;                 *(LDS_AS u32x2*)(lb + VOFF + hd * HSTR + r * 144 + d * 2) = (u32x2){pk2(tv[i][0], tv[i][1]), pk2(tv[i][2], tv[i][3])};
;             }
;             if (MODE == 1 && tid < 256) *(LDS_AS float*)(lb + BOFF + tid * 4) = cref - tb;
;             if (it > 0) {
;                 const float* kg = ck + (size_t)kposn * 512;
;                 const float* vg = cv + (size_t)kposn * 512;
;                 if (MODE == 1 && tid < 256) tb = cseq[kposn + (tid & 31)];
; #pragma unroll
;                 for (int i = 0; i < 8; ++i) { const int id = tid + 512 * i; tk[i] = __builtin_nontemporal_load((const f32x4*)(kg + (size_t)id * 4)); tv[i] = __builtin_nontemporal_load((const f32x4*)(vg + (size_t)id * 4)); }
;             }
.LBB0_496:
	s_waitcnt vmcnt(14)
	v_cvt_pk_bf16_f32 v32, v64, v65
	v_cvt_pk_bf16_f32 v33, v66, v67
	v_cvt_pk_bf16_f32 v34, v68, v69
	v_cvt_pk_bf16_f32 v35, v70, v71
	s_barrier
	ds_write2st64_b64 v178, v[32:33], v[34:35] offset1:72
	s_waitcnt vmcnt(11)
	v_cvt_pk_bf16_f32 v32, v72, v73
	v_cvt_pk_bf16_f32 v33, v74, v75
	v_cvt_pk_bf16_f32 v34, v76, v77
	v_cvt_pk_bf16_f32 v35, v78, v79
	ds_write2st64_b64 v179, v[32:33], v[34:35] offset1:72
	s_waitcnt vmcnt(9)
	v_cvt_pk_bf16_f32 v32, v80, v81
	v_cvt_pk_bf16_f32 v33, v82, v83
	v_cvt_pk_bf16_f32 v34, v84, v85
	v_cvt_pk_bf16_f32 v35, v86, v87
	ds_write2st64_b64 v180, v[32:33], v[34:35] offset1:72
	s_waitcnt vmcnt(7)
	v_cvt_pk_bf16_f32 v32, v88, v89
	v_cvt_pk_bf16_f32 v33, v90, v91
	v_cvt_pk_bf16_f32 v34, v92, v93
	v_cvt_pk_bf16_f32 v35, v94, v95
	ds_write2st64_b64 v181, v[32:33], v[34:35] offset1:72
	s_waitcnt vmcnt(5)
	v_cvt_pk_bf16_f32 v32, v96, v97
	v_cvt_pk_bf16_f32 v33, v98, v99
	v_cvt_pk_bf16_f32 v34, v100, v101
	v_cvt_pk_bf16_f32 v35, v102, v103
	ds_write2st64_b64 v182, v[32:33], v[34:35] offset1:72
	s_waitcnt vmcnt(3)
	v_cvt_pk_bf16_f32 v32, v104, v105
	v_cvt_pk_bf16_f32 v33, v106, v107
	v_cvt_pk_bf16_f32 v34, v108, v109
	v_cvt_pk_bf16_f32 v35, v110, v111
	s_cmp_eq_u32 s46, 0x1fc000
	ds_write2st64_b64 v183, v[32:33], v[34:35] offset1:72
	s_waitcnt vmcnt(2)
	v_cvt_pk_bf16_f32 v32, v112, v113
	v_cvt_pk_bf16_f32 v33, v114, v115
	s_waitcnt vmcnt(1)
	v_cvt_pk_bf16_f32 v34, v116, v117
	v_cvt_pk_bf16_f32 v35, v118, v119
	s_cselect_b64 s[30:31], -1, 0
	ds_write2st64_b64 v184, v[32:33], v[34:35] offset1:72
	v_cvt_pk_bf16_f32 v32, v120, v121
	v_cvt_pk_bf16_f32 v33, v122, v123
	s_waitcnt vmcnt(0)
	v_cvt_pk_bf16_f32 v34, v124, v125
	v_cvt_pk_bf16_f32 v35, v126, v127
	s_and_b64 vcc, exec, s[30:31]
	ds_write2st64_b64 v185, v[32:33], v[34:35] offset1:72
	s_cbranch_vccnz .LBB0_498
	s_and_b32 s36, s46, 0x1fc000
	s_lshl_b32 s47, s36, 2
	s_add_u32 s36, s10, s47
	s_addc_u32 s37, s39, 0
	s_add_u32 s48, s42, s47
	s_addc_u32 s49, s43, 0
	v_lshl_add_u64 v[32:33], s[36:37], 0, v[148:149]
	global_load_dwordx4 v[64:67], v[32:33], off sc0 sc1 nt
	v_lshl_add_u64 v[32:33], s[48:49], 0, v[148:149]
	global_load_dwordx4 v[68:71], v[32:33], off sc0 sc1 nt
	v_lshl_add_u64 v[32:33], s[36:37], 0, v[150:151]
	global_load_dwordx4 v[72:75], v[32:33], off sc0 sc1 nt
	v_lshl_add_u64 v[32:33], s[48:49], 0, v[150:151]
	global_load_dwordx4 v[76:79], v[32:33], off sc0 sc1 nt
	v_lshl_add_u64 v[32:33], s[36:37], 0, v[152:153]
	global_load_dwordx4 v[80:83], v[32:33], off sc0 sc1 nt
	v_lshl_add_u64 v[32:33], s[48:49], 0, v[152:153]
	global_load_dwordx4 v[84:87], v[32:33], off sc0 sc1 nt
	v_lshl_add_u64 v[32:33], s[36:37], 0, v[154:155]
	global_load_dwordx4 v[88:91], v[32:33], off sc0 sc1 nt
	v_lshl_add_u64 v[32:33], s[48:49], 0, v[154:155]
	global_load_dwordx4 v[92:95], v[32:33], off sc0 sc1 nt
	v_lshl_add_u64 v[32:33], s[36:37], 0, v[156:157]
	global_load_dwordx4 v[96:99], v[32:33], off sc0 sc1 nt
	v_lshl_add_u64 v[32:33], s[48:49], 0, v[156:157]
	global_load_dwordx4 v[100:103], v[32:33], off sc0 sc1 nt
	v_lshl_add_u64 v[32:33], s[36:37], 0, v[158:159]
	global_load_dwordx4 v[104:107], v[32:33], off sc0 sc1 nt
	v_lshl_add_u64 v[32:33], s[48:49], 0, v[158:159]
	global_load_dwordx4 v[108:111], v[32:33], off sc0 sc1 nt
	v_lshl_add_u64 v[32:33], s[36:37], 0, v[160:161]
	global_load_dwordx4 v[112:115], v[32:33], off sc0 sc1 nt
	v_lshl_add_u64 v[32:33], s[48:49], 0, v[160:161]
	global_load_dwordx4 v[116:119], v[32:33], off sc0 sc1 nt
	v_lshl_add_u64 v[32:33], s[36:37], 0, v[162:163]
	global_load_dwordx4 v[120:123], v[32:33], off sc0 sc1 nt
	v_lshl_add_u64 v[32:33], s[48:49], 0, v[162:163]
	global_load_dwordx4 v[124:127], v[32:33], off sc0 sc1 nt

;     DI void operator()(const f32x4 (&acc)[2][2][4][2], const pg8::Unit& u, int wr, int wc, int fr, int fq) const {
;     ...
;         for (int ai = 0; ai < 2; ++ai)
; #pragma unroll
;             for (int m = 0; m < 4; ++m) {
;                 const int R = u.pm * 256 + ai * 128 + wr * 64 + m * 16 + fr;
;                 const float* xs = nullptr; float* yd = nullptr;
;                 if (R < ROWS_P) { const int b = R / LPAD, t = R - b * LPAD; if (t >= NMETA && t < LP) { const size_t idx = ((size_t)b * SEQ + t - NMETA) * DM; xs = p.x_prompt + idx; yd = p.out + O_YP + idx; } }
;                 else { const size_t idx = (size_t)(R - ROWS_P) * DM; xs = p.x_sample + idx; yd = p.out + O_YS + idx; }
;                 float ss = 0.f;
;                 if (xs) {
; #pragma unroll
;                     for (int bj = 0; bj < 2; ++bj) {
;                         const int n = colt + bj * 128 + wc * 32 + 8 * fq;
;                         const f32x4 x0 = *(const f32x4*)(xs + n), x1 = *(const f32x4*)(xs + n + 4);
;                         const f32x4 h0 = x0 + acc[ai][bj][m][0], h1 = x1 + acc[ai][bj][m][1];
;                         *(f32x4*)(yd + n) = h0; *(f32x4*)(yd + n + 4) = h1;
;                         ss += h0[0] * h0[0] + h0[1] * h0[1] + h0[2] * h0[2] + h0[3] * h0[3] + h1[0] * h1[0] + h1[1] * h1[1] + h1[2] * h1[2] + h1[3] * h1[3];
;                     }
.LBB0_620:
	s_cmp_eq_u32 s100, 15
	s_cbranch_scc0 .Lp3q_epi
	v_lshl_add_u32 v150, s94, 8, v158
	v_lshl_or_b32 v155, s42, 8, v159
	v_and_b32_e32 v151, 15, v158
	v_lshlrev_b32_e32 v155, 2, v155
	v_lshl_or_b32 v151, v151, 12, v155
	v_lshlrev_b32_e32 v152, 2, v150
	v_mov_b32_e32 v150, v155
	v_xor_b32_e32 v153, 16, v174
	v_xor_b32_e32 v154, 32, v174
	v_lshlrev_b32_e32 v153, 2, v153
	v_lshlrev_b32_e32 v154, 2, v154
	s_and_b64 s[20:21], s[72:73], exec
	s_cselect_b32 s20, 64, 0
	s_lshl_b32 s21, s94, 8
	s_add_i32 s21, s21, s20
	s_cmp_ge_u32 s94, 65
	s_cselect_b32 s96, s78, s76
	s_cselect_b32 s97, s79, s77
	s_cselect_b32 s98, s82, s54
	s_cselect_b32 s99, s83, s55
	s_mov_b32 s19, 0
	s_add_i32 s87, s21, 0
	s_mul_hi_u32 s89, s87, 0x7e07e07f
	s_lshr_b32 s89, s89, 11
	s_mul_i32 vcc_lo, s89, 0x1040
	s_sub_i32 vcc_lo, s87, vcc_lo
	s_add_i32 vcc_lo, vcc_lo, -16
	s_lshl_b32 s89, s89, 12
	s_add_i32 s89, s89, vcc_lo
	s_cmp_lt_u32 vcc_lo, 0x1000
	s_cselect_b32 vcc_hi, 1, 0
	s_sub_i32 vcc_lo, s87, 0x4100
	s_cmp_ge_u32 s94, 65
	s_cselect_b32 s89, vcc_lo, s89
	s_cselect_b32 vcc_hi, 1, vcc_hi
	s_cmp_lg_u32 vcc_hi, 0
	s_cselect_b32 s89, s89, 0
	s_lshl_b32 s20, s89, 12
	s_lshl_b32 vcc_hi, vcc_hi, 0
	s_or_b32 s19, s19, vcc_hi
	s_add_u32 s22, s96, s20
	s_addc_u32 s23, s97, 0
	global_load_dwordx4 v[176:179], v151, s[22:23] sc0 sc1 nt
	global_load_dwordx4 v[180:183], v151, s[22:23] offset:16 sc0 sc1 nt
	global_load_dwordx4 v[184:187], v151, s[22:23] offset:512 sc0 sc1 nt
	global_load_dwordx4 v[188:191], v151, s[22:23] offset:528 sc0 sc1 nt
	s_add_i32 s87, s21, 16
	s_mul_hi_u32 s89, s87, 0x7e07e07f
	s_lshr_b32 s89, s89, 11
	s_mul_i32 vcc_lo, s89, 0x1040
	s_sub_i32 vcc_lo, s87, vcc_lo
	s_add_i32 vcc_lo, vcc_lo, -16
	s_lshl_b32 s89, s89, 12
	s_add_i32 s89, s89, vcc_lo
	s_cmp_lt_u32 vcc_lo, 0x1000
	s_cselect_b32 vcc_hi, 1, 0
	s_sub_i32 vcc_lo, s87, 0x4100
	s_cmp_ge_u32 s94, 65
	s_cselect_b32 s89, vcc_lo, s89
	s_cselect_b32 vcc_hi, 1, vcc_hi
	s_cmp_lg_u32 vcc_hi, 0
	s_cselect_b32 s89, s89, 0
	s_lshl_b32 s42, s89, 12
	s_lshl_b32 vcc_hi, vcc_hi, 1
	s_or_b32 s19, s19, vcc_hi
	s_add_u32 s22, s96, s42
	s_addc_u32 s23, s97, 0
	global_load_dwordx4 v[192:195], v151, s[22:23] sc0 sc1 nt
	global_load_dwordx4 v[196:199], v151, s[22:23] offset:16 sc0 sc1 nt
	global_load_dwordx4 v[200:203], v151, s[22:23] offset:512 sc0 sc1 nt
	global_load_dwordx4 v[204:207], v151, s[22:23] offset:528 sc0 sc1 nt
	s_add_i32 s87, s21, 32
	s_mul_hi_u32 s89, s87, 0x7e07e07f
	s_lshr_b32 s89, s89, 11
	s_mul_i32 vcc_lo, s89, 0x1040
	s_sub_i32 vcc_lo, s87, vcc_lo
	s_add_i32 vcc_lo, vcc_lo, -16
	s_lshl_b32 s89, s89, 12
	s_add_i32 s89, s89, vcc_lo
	s_cmp_lt_u32 vcc_lo, 0x1000
	s_cselect_b32 vcc_hi, 1, 0
	s_sub_i32 vcc_lo, s87, 0x4100
	s_cmp_ge_u32 s94, 65
	s_cselect_b32 s89, vcc_lo, s89
	s_cselect_b32 vcc_hi, 1, vcc_hi
	s_cmp_lg_u32 vcc_hi, 0
	s_cselect_b32 s89, s89, 0
	s_lshl_b32 s43, s89, 12
	s_lshl_b32 vcc_hi, vcc_hi, 2
	s_or_b32 s19, s19, vcc_hi
	s_add_u32 s22, s96, s43
	s_addc_u32 s23, s97, 0
	global_load_dwordx4 v[208:211], v151, s[22:23] sc0 sc1 nt
	global_load_dwordx4 v[212:215], v151, s[22:23] offset:16 sc0 sc1 nt
	global_load_dwordx4 v[216:219], v151, s[22:23] offset:512 sc0 sc1 nt
	global_load_dwordx4 v[220:223], v151, s[22:23] offset:528 sc0 sc1 nt
	s_add_i32 s87, s21, 48
	s_mul_hi_u32 s89, s87, 0x7e07e07f
	s_lshr_b32 s89, s89, 11
	s_mul_i32 vcc_lo, s89, 0x1040
	s_sub_i32 vcc_lo, s87, vcc_lo
	s_add_i32 vcc_lo, vcc_lo, -16
	s_lshl_b32 s89, s89, 12
	s_add_i32 s89, s89, vcc_lo
	s_cmp_lt_u32 vcc_lo, 0x1000
	s_cselect_b32 vcc_hi, 1, 0
	s_sub_i32 vcc_lo, s87, 0x4100
	s_cmp_ge_u32 s94, 65
	s_cselect_b32 s89, vcc_lo, s89
	s_cselect_b32 vcc_hi, 1, vcc_hi
	s_cmp_lg_u32 vcc_hi, 0
	s_cselect_b32 s89, s89, 0
	s_lshl_b32 s95, s89, 12
	s_lshl_b32 vcc_hi, vcc_hi, 3
	s_or_b32 s19, s19, vcc_hi
	s_add_u32 s22, s96, s95
	s_addc_u32 s23, s97, 0
	global_load_dwordx4 v[224:227], v151, s[22:23] sc0 sc1 nt
	global_load_dwordx4 v[228:231], v151, s[22:23] offset:16 sc0 sc1 nt
	global_load_dwordx4 v[232:235], v151, s[22:23] offset:512 sc0 sc1 nt
	global_load_dwordx4 v[236:239], v151, s[22:23] offset:528 sc0 sc1 nt
	s_waitcnt vmcnt(0)
	v_pk_add_f32 v[124:125], v[124:125], v[176:177]
	v_pk_add_f32 v[126:127], v[126:127], v[178:179]
	v_pk_add_f32 v[120:121], v[120:121], v[180:181]
	v_pk_add_f32 v[122:123], v[122:123], v[182:183]
	v_pk_add_f32 v[116:117], v[116:117], v[184:185]
	v_pk_add_f32 v[118:119], v[118:119], v[186:187]
	v_pk_add_f32 v[112:113], v[112:113], v[188:189]
	v_pk_add_f32 v[114:115], v[114:115], v[190:191]
	v_pk_mul_f32 v[172:173], v[124:125], v[124:125]
	v_pk_fma_f32 v[172:173], v[126:127], v[126:127], v[172:173]
	v_pk_fma_f32 v[172:173], v[120:121], v[120:121], v[172:173]
	v_pk_fma_f32 v[172:173], v[122:123], v[122:123], v[172:173]
	v_pk_fma_f32 v[172:173], v[116:117], v[116:117], v[172:173]
	v_pk_fma_f32 v[172:173], v[118:119], v[118:119], v[172:173]
	v_pk_fma_f32 v[172:173], v[112:113], v[112:113], v[172:173]
	v_pk_fma_f32 v[172:173], v[114:115], v[114:115], v[172:173]
	s_nop 0
	v_add_f32_e32 v168, v172, v173
	s_add_i32 s87, s21, 128
	s_mul_hi_u32 s89, s87, 0x7e07e07f
	s_lshr_b32 s89, s89, 11
	s_mul_i32 vcc_lo, s89, 0x1040
	s_sub_i32 vcc_lo, s87, vcc_lo
	s_add_i32 vcc_lo, vcc_lo, -16
	s_lshl_b32 s89, s89, 12
	s_add_i32 s89, s89, vcc_lo
	s_cmp_lt_u32 vcc_lo, 0x1000
	s_cselect_b32 vcc_hi, 1, 0
	s_sub_i32 vcc_lo, s87, 0x4100
	s_cmp_ge_u32 s94, 65
	s_cselect_b32 s89, vcc_lo, s89
	s_cselect_b32 vcc_hi, 1, vcc_hi
	s_cmp_lg_u32 vcc_hi, 0
	s_cselect_b32 s89, s89, 0
	s_lshl_b32 s20, s89, 12
	s_lshl_b32 vcc_hi, vcc_hi, 4
	s_or_b32 s19, s19, vcc_hi
	s_add_u32 s22, s96, s20
	s_addc_u32 s23, s97, 0
;     DI void operator()(const f32x4 (&acc)[2][2][4][2], const pg8::Unit& u, int wr, int wc, int fr, int fq) const {
;     ...
;                 float ss = 0.f;
;                 if (xs) {
; #pragma unroll
;                     for (int bj = 0; bj < 2; ++bj) {
;                         const int n = colt + bj * 128 + wc * 32 + 8 * fq;
;                         const f32x4 x0 = *(const f32x4*)(xs + n), x1 = *(const f32x4*)(xs + n + 4);
;                         const f32x4 h0 = x0 + acc[ai][bj][m][0], h1 = x1 + acc[ai][bj][m][1];
;                         *(f32x4*)(yd + n) = h0; *(f32x4*)(yd + n + 4) = h1;
;                         ss += h0[0] * h0[0] + h0[1] * h0[1] + h0[2] * h0[2] + h0[3] * h0[3] + h1[0] * h1[0] + h1[1] * h1[1] + h1[2] * h1[2] + h1[3] * h1[3];
;                     }
;                 }
;                 ss += __shfl_xor(ss, 16); ss += __shfl_xor(ss, 32);
;                 if (xs && fq == 0) atomicAdd(p.rowss + R, ss);
	global_load_dwordx4 v[176:179], v151, s[22:23] sc0 sc1 nt
	global_load_dwordx4 v[180:183], v151, s[22:23] offset:16 sc0 sc1 nt
	global_load_dwordx4 v[184:187], v151, s[22:23] offset:512 sc0 sc1 nt
	global_load_dwordx4 v[188:191], v151, s[22:23] offset:528 sc0 sc1 nt
	v_pk_add_f32 v[108:109], v[108:109], v[192:193]
	v_pk_add_f32 v[110:111], v[110:111], v[194:195]
	v_pk_add_f32 v[104:105], v[104:105], v[196:197]
	v_pk_add_f32 v[106:107], v[106:107], v[198:199]
	v_pk_add_f32 v[100:101], v[100:101], v[200:201]
	v_pk_add_f32 v[102:103], v[102:103], v[202:203]
	v_pk_add_f32 v[96:97], v[96:97], v[204:205]
	v_pk_add_f32 v[98:99], v[98:99], v[206:207]
	v_pk_mul_f32 v[172:173], v[108:109], v[108:109]
	v_pk_fma_f32 v[172:173], v[110:111], v[110:111], v[172:173]
	v_pk_fma_f32 v[172:173], v[104:105], v[104:105], v[172:173]
	v_pk_fma_f32 v[172:173], v[106:107], v[106:107], v[172:173]
	v_pk_fma_f32 v[172:173], v[100:101], v[100:101], v[172:173]
	v_pk_fma_f32 v[172:173], v[102:103], v[102:103], v[172:173]
	v_pk_fma_f32 v[172:173], v[96:97], v[96:97], v[172:173]
	v_pk_fma_f32 v[172:173], v[98:99], v[98:99], v[172:173]
	s_nop 0
	v_add_f32_e32 v169, v172, v173
	s_add_i32 s87, s21, 144
	s_mul_hi_u32 s89, s87, 0x7e07e07f
	s_lshr_b32 s89, s89, 11
	s_mul_i32 vcc_lo, s89, 0x1040
	s_sub_i32 vcc_lo, s87, vcc_lo
	s_add_i32 vcc_lo, vcc_lo, -16
	s_lshl_b32 s89, s89, 12
	s_add_i32 s89, s89, vcc_lo
	s_cmp_lt_u32 vcc_lo, 0x1000
	s_cselect_b32 vcc_hi, 1, 0
	s_sub_i32 vcc_lo, s87, 0x4100
	s_cmp_ge_u32 s94, 65
	s_cselect_b32 s89, vcc_lo, s89
	s_cselect_b32 vcc_hi, 1, vcc_hi
	s_cmp_lg_u32 vcc_hi, 0
	s_cselect_b32 s89, s89, 0
	s_lshl_b32 s42, s89, 12
	s_lshl_b32 vcc_hi, vcc_hi, 5
	s_or_b32 s19, s19, vcc_hi
	s_add_u32 s22, s96, s42
	s_addc_u32 s23, s97, 0
	global_load_dwordx4 v[192:195], v151, s[22:23] sc0 sc1 nt
	global_load_dwordx4 v[196:199], v151, s[22:23] offset:16 sc0 sc1 nt
	global_load_dwordx4 v[200:203], v151, s[22:23] offset:512 sc0 sc1 nt
	global_load_dwordx4 v[204:207], v151, s[22:23] offset:528 sc0 sc1 nt
	v_pk_add_f32 v[92:93], v[92:93], v[208:209]
	v_pk_add_f32 v[94:95], v[94:95], v[210:211]
	v_pk_add_f32 v[88:89], v[88:89], v[212:213]
	v_pk_add_f32 v[90:91], v[90:91], v[214:215]
	v_pk_add_f32 v[84:85], v[84:85], v[216:217]
	v_pk_add_f32 v[86:87], v[86:87], v[218:219]
	v_pk_add_f32 v[80:81], v[80:81], v[220:221]
	v_pk_add_f32 v[82:83], v[82:83], v[222:223]
	v_pk_mul_f32 v[172:173], v[92:93], v[92:93]
	v_pk_fma_f32 v[172:173], v[94:95], v[94:95], v[172:173]
	v_pk_fma_f32 v[172:173], v[88:89], v[88:89], v[172:173]
	v_pk_fma_f32 v[172:173], v[90:91], v[90:91], v[172:173]
	v_pk_fma_f32 v[172:173], v[84:85], v[84:85], v[172:173]
	v_pk_fma_f32 v[172:173], v[86:87], v[86:87], v[172:173]
	v_pk_fma_f32 v[172:173], v[80:81], v[80:81], v[172:173]
	v_pk_fma_f32 v[172:173], v[82:83], v[82:83], v[172:173]
	s_nop 0
	v_add_f32_e32 v170, v172, v173
	s_add_i32 s87, s21, 160
	s_mul_hi_u32 s89, s87, 0x7e07e07f
	s_lshr_b32 s89, s89, 11
	s_mul_i32 vcc_lo, s89, 0x1040
	s_sub_i32 vcc_lo, s87, vcc_lo
	s_add_i32 vcc_lo, vcc_lo, -16
	s_lshl_b32 s89, s89, 12
	s_add_i32 s89, s89, vcc_lo
	s_cmp_lt_u32 vcc_lo, 0x1000
	s_cselect_b32 vcc_hi, 1, 0
	s_sub_i32 vcc_lo, s87, 0x4100
	s_cmp_ge_u32 s94, 65
	s_cselect_b32 s89, vcc_lo, s89
	s_cselect_b32 vcc_hi, 1, vcc_hi
	s_cmp_lg_u32 vcc_hi, 0
	s_cselect_b32 s89, s89, 0
	s_lshl_b32 s43, s89, 12
	s_lshl_b32 vcc_hi, vcc_hi, 6
	s_or_b32 s19, s19, vcc_hi
	s_add_u32 s22, s96, s43
	s_addc_u32 s23, s97, 0
	global_load_dwordx4 v[208:211], v151, s[22:23] sc0 sc1 nt
	global_load_dwordx4 v[212:215], v151, s[22:23] offset:16 sc0 sc1 nt
	global_load_dwordx4 v[216:219], v151, s[22:23] offset:512 sc0 sc1 nt
	global_load_dwordx4 v[220:223], v151, s[22:23] offset:528 sc0 sc1 nt
	v_pk_add_f32 v[76:77], v[76:77], v[224:225]
	v_pk_add_f32 v[78:79], v[78:79], v[226:227]
	v_pk_add_f32 v[72:73], v[72:73], v[228:229]
	v_pk_add_f32 v[74:75], v[74:75], v[230:231]
	v_pk_add_f32 v[68:69], v[68:69], v[232:233]
	v_pk_add_f32 v[70:71], v[70:71], v[234:235]
	v_pk_add_f32 v[64:65], v[64:65], v[236:237]
	v_pk_add_f32 v[66:67], v[66:67], v[238:239]
	v_pk_mul_f32 v[172:173], v[76:77], v[76:77]
	v_pk_fma_f32 v[172:173], v[78:79], v[78:79], v[172:173]
	v_pk_fma_f32 v[172:173], v[72:73], v[72:73], v[172:173]
	v_pk_fma_f32 v[172:173], v[74:75], v[74:75], v[172:173]
	v_pk_fma_f32 v[172:173], v[68:69], v[68:69], v[172:173]
	v_pk_fma_f32 v[172:173], v[70:71], v[70:71], v[172:173]
	v_pk_fma_f32 v[172:173], v[64:65], v[64:65], v[172:173]
	v_pk_fma_f32 v[172:173], v[66:67], v[66:67], v[172:173]
	s_nop 0
	v_add_f32_e32 v171, v172, v173
	s_add_i32 s87, s21, 176
	s_mul_hi_u32 s89, s87, 0x7e07e07f
	s_lshr_b32 s89, s89, 11
	s_mul_i32 vcc_lo, s89, 0x1040
	s_sub_i32 vcc_lo, s87, vcc_lo
	s_add_i32 vcc_lo, vcc_lo, -16
	s_lshl_b32 s89, s89, 12
	s_add_i32 s89, s89, vcc_lo
	s_cmp_lt_u32 vcc_lo, 0x1000
	s_cselect_b32 vcc_hi, 1, 0
	s_sub_i32 vcc_lo, s87, 0x4100
	s_cmp_ge_u32 s94, 65
	s_cselect_b32 s89, vcc_lo, s89
	s_cselect_b32 vcc_hi, 1, vcc_hi
	s_cmp_lg_u32 vcc_hi, 0
	s_cselect_b32 s89, s89, 0
	s_lshl_b32 s95, s89, 12
	s_lshl_b32 vcc_hi, vcc_hi, 7
	s_or_b32 s19, s19, vcc_hi
	s_add_u32 s22, s96, s95
	s_addc_u32 s23, s97, 0
	global_load_dwordx4 v[224:227], v151, s[22:23] sc0 sc1 nt
	global_load_dwordx4 v[228:231], v151, s[22:23] offset:16 sc0 sc1 nt
	global_load_dwordx4 v[232:235], v151, s[22:23] offset:512 sc0 sc1 nt
	global_load_dwordx4 v[236:239], v151, s[22:23] offset:528 sc0 sc1 nt
	ds_bpermute_b32 v155, v153, v168
	ds_bpermute_b32 v156, v153, v169
	ds_bpermute_b32 v157, v153, v170
	ds_bpermute_b32 v132, v153, v171
	s_waitcnt lgkmcnt(0)
	v_add_f32_e32 v168, v168, v155
	v_add_f32_e32 v169, v169, v156
	v_add_f32_e32 v170, v170, v157
	v_add_f32_e32 v171, v171, v132
	ds_bpermute_b32 v155, v154, v168
	ds_bpermute_b32 v156, v154, v169
	ds_bpermute_b32 v157, v154, v170
	ds_bpermute_b32 v132, v154, v171
	s_waitcnt lgkmcnt(0)
	v_add_f32_e32 v168, v168, v155
	v_add_f32_e32 v169, v169, v156
	v_add_f32_e32 v170, v170, v157
	v_add_f32_e32 v171, v171, v132
	s_mov_b64 exec, s[36:37]
	s_bitcmp1_b32 s19, 0
	s_cbranch_scc0 .Lf3f_at_b0_0
	global_atomic_add_f32 v152, v168, s[60:61]
